# cand34 + prompt attention units: sink and first Q-fragment loads requested at the unit start, ahead of the K/V tile loads
# baseline (speedup 1.0000x reference)
.LBB0_1402:
	s_bfe_u32 s58, s57, 0x30004
	s_lshl_b32 s28, s58, 9
	s_add_i32 s38, s52, s28
	s_ashr_i32 s46, s57, 7
	s_ashr_i32 s39, s38, 31
	s_ashr_i32 s47, s46, 31
	s_lshl_b64 s[38:39], s[38:39], 1
	s_and_b32 s28, s57, 15
	s_lshl_b64 s[48:49], s[46:47], 11
	s_cmp_lg_u32 s28, 0
	s_cbranch_scc0 .LBB0_1408
	s_lshl_b32 s98, s58, 3
	s_add_i32 s98, s98, s41
	s_ashr_i32 s99, s98, 31
	s_lshl_b64 s[98:99], s[98:99], 2
	s_add_u32 s98, s44, s98
	s_addc_u32 s99, s45, s99
	global_load_dword v5, v4, s[98:99]
	s_and_b32 s82, s56, 15
	s_lshl_b32 s82, s82, 7
	s_add_u32 s100, s82, s48
	s_addc_u32 s101, 0, s49
	v_mov_b64_e32 v[38:39], s[38:39]
	v_lshl_add_u64 v[40:41], s[100:101], 0, v[56:57]
	v_mad_u64_u32 v[38:39], s[100:101], v40, s53, v[38:39]
	v_lshlrev_b64 v[42:43], 13, v[40:41]
	v_mad_i32_i24 v39, v41, s53, v39
	v_lshl_add_u64 v[44:45], v[74:75], 0, v[38:39]
	global_load_dwordx4 v[180:183], v[44:45], off offset:-64
	global_load_dwordx4 v[184:187], v[44:45], off
	s_lshl_b32 s28, s28, 7
	s_or_b32 s28, s48, s28
	s_add_u32 s50, s28, 0xffffff80
	s_addc_u32 s51, s49, -1
	v_lshl_add_u64 v[2:3], s[50:51], 0, v[58:59]
	v_mov_b64_e32 v[30:31], s[26:27]
	v_mad_u64_u32 v[6:7], s[60:61], v2, s53, v[30:31]
	v_mad_i32_i24 v7, v3, s53, v7
	s_lshl_b32 s28, s58, 7
	v_lshl_add_u64 v[2:3], v[6:7], 0, s[28:29]
	v_mov_b32_e32 v83, v4
	v_lshl_add_u64 v[2:3], v[2:3], 0, v[82:83]
	v_lshl_add_u64 v[6:7], v[2:3], 0, s[30:31]
	v_add_co_u32_e32 v2, vcc, s54, v2
	s_nop 1
	v_addc_co_u32_e32 v3, vcc, 0, v3, vcc
	global_load_dwordx4 v[6:9], v[6:7], off offset:1024
	s_nop 0
	global_load_dwordx4 v[10:13], v[2:3], off
	v_lshl_add_u64 v[2:3], s[50:51], 0, v[60:61]
	v_mad_u64_u32 v[14:15], s[60:61], v2, s53, v[30:31]
	v_mad_i32_i24 v15, v3, s53, v15
	v_lshl_add_u64 v[2:3], v[14:15], 0, s[28:29]
	v_lshl_add_u64 v[2:3], v[2:3], 0, v[82:83]
	v_lshl_add_u64 v[14:15], v[2:3], 0, s[30:31]
	v_add_co_u32_e32 v2, vcc, s54, v2
	s_nop 1
	v_addc_co_u32_e32 v3, vcc, 0, v3, vcc
	global_load_dwordx4 v[14:17], v[14:15], off offset:1024
	s_nop 0
	global_load_dwordx4 v[18:21], v[2:3], off
	v_lshl_add_u64 v[2:3], s[50:51], 0, v[62:63]
	v_mad_u64_u32 v[22:23], s[60:61], v2, s53, v[30:31]
	v_mad_i32_i24 v23, v3, s53, v23
	v_lshl_add_u64 v[2:3], v[22:23], 0, s[28:29]
	v_lshl_add_u64 v[2:3], v[2:3], 0, v[82:83]
	v_lshl_add_u64 v[22:23], v[2:3], 0, s[30:31]
	v_add_co_u32_e32 v2, vcc, s54, v2
	s_nop 1
	v_addc_co_u32_e32 v3, vcc, 0, v3, vcc
	global_load_dwordx4 v[22:25], v[22:23], off offset:1024
	s_nop 0
	global_load_dwordx4 v[26:29], v[2:3], off
	v_lshl_add_u64 v[2:3], s[50:51], 0, v[64:65]
	v_mad_u64_u32 v[30:31], s[50:51], v2, s53, v[30:31]
	v_mad_i32_i24 v31, v3, s53, v31
	v_lshl_add_u64 v[2:3], v[30:31], 0, s[28:29]
	v_lshl_add_u64 v[2:3], v[2:3], 0, v[82:83]
	v_lshl_add_u64 v[34:35], v[2:3], 0, s[30:31]
	v_add_co_u32_e32 v2, vcc, 0x2000, v2
	s_nop 1
	v_addc_co_u32_e32 v3, vcc, 0, v3, vcc
	global_load_dwordx4 v[30:33], v[2:3], off
	s_nop 0
	global_load_dwordx4 v[34:37], v[34:35], off offset:1024
	s_waitcnt vmcnt(6)
	ds_write_b128 v92, v[10:13]
	ds_write_b128 v92, v[6:9] offset:36864
	s_waitcnt vmcnt(4)
	ds_write_b128 v93, v[18:21]
	ds_write_b128 v93, v[14:17] offset:36864
	s_waitcnt vmcnt(3)
	ds_write_b128 v94, v[22:25] offset:36864
	s_waitcnt vmcnt(2)
	ds_write_b128 v94, v[26:29]
	s_waitcnt vmcnt(1)
	ds_write_b128 v95, v[30:33]
	s_waitcnt vmcnt(0)
	ds_write_b128 v95, v[34:37] offset:36864
	s_and_saveexec_b64 s[50:51], s[0:1]
	v_add_u32_e32 v2, v55, v88
	ds_write_b128 v2, v[100:103] offset:36864
	s_or_b64 exec, exec, s[50:51]
	s_and_b32 s28, s56, 15
	s_lshl_b32 s59, s28, 7
	s_lshl_b32 s28, s58, 3
	s_add_i32 s50, s28, s41
	s_ashr_i32 s51, s50, 31
	s_lshl_b64 s[50:51], s[50:51], 2
	s_add_u32 s50, s44, s50
	s_addc_u32 s51, s45, s51
	s_waitcnt lgkmcnt(0)
	s_barrier
	v_and_b32_e32 v7, 64, v96
	v_xor_b32_e32 v6, 16, v96
	v_add_u32_e32 v7, 64, v7
	v_xor_b32_e32 v8, 32, v96
	v_cmp_lt_i32_e32 vcc, v6, v7
	s_add_u32 s50, s59, s48
	s_addc_u32 s51, 0, s49
	v_cndmask_b32_e32 v6, v96, v6, vcc
	v_cmp_lt_i32_e32 vcc, v8, v7
	v_mov_b64_e32 v[2:3], s[38:39]
	v_lshlrev_b32_e32 v83, 2, v6
	v_cndmask_b32_e32 v7, v96, v8, vcc
	v_lshlrev_b32_e32 v98, 2, v7
	v_lshl_add_u64 v[6:7], s[50:51], 0, v[56:57]
	v_mad_u64_u32 v[2:3], s[50:51], v6, s53, v[2:3]
	v_lshlrev_b64 v[8:9], 13, v[6:7]
	v_mad_i32_i24 v3, v7, s53, v3
	v_lshl_add_u64 v[6:7], v[8:9], 0, s[38:39]
	s_mov_b32 s28, 0
	v_lshl_add_u64 v[84:85], v[74:75], 0, v[2:3]
	v_lshl_add_u64 v[86:87], v[76:77], 0, v[6:7]
	v_lshl_add_u64 v[84:85], v[84:85], 0, s[34:35]
	s_waitcnt vmcnt(0)
	v_mul_f32_e32 v99, 0x3fb8aa3b, v5
	s_branch .Lattq_entry_A
